# v9 + static s_setprio 1 for waves 4-7 during attention and retc phases (strategy 4: one static priority raise for the younger half)
# baseline (speedup 1.0000x reference)
; __device__ __forceinline__ void attn_stream(const int wv, LAS unsigned char* lds, unsigned ldsb, const float* __restrict__ qng, const float* __restrict__ kng, const bf16_t* __restrict__ qkvr, bf16_t* __restrict__ og, float* __restrict__ lse, ...
;     int t_ = TIDX; asm volatile("" : "+v"(t_));
;     const int t = t_, w = __builtin_amdgcn_readfirstlane(t >> 6), lane = t & 63, li = lane & 15, g = lane >> 4;
;     if (first >= count) return;
;     const unsigned QI = 0, KI = 128 * PA;
;     const int c16 = t & 15, c160 = t & 15, rr0 = t >> 4, rr = t >> 4;
;     u32x4 qr[4], kr[8], vr[8];
;     ...
;     int item = first;
;     ATTN_LOAD_QK(item);
.LBB0_310:
	s_or_b64 exec, exec, s[0:1]
	s_mov_b64 s[2:3], s[56:57]
	v_readlane_b32 s0, v253, 40
	s_waitcnt lgkmcnt(0)
	s_barrier
	s_cmpk_lt_u32 s53, 0x100
	s_cbranch_scc1 .Lprio_a
	s_setprio 1
.Lprio_a:
	v_mbcnt_lo_u32_b32 v1, -1, 0
	v_mbcnt_hi_u32_b32 v1, -1, v1
	v_readlane_b32 s1, v253, 41
	v_add_u32_e32 v54, s53, v1
	s_andn2_b64 vcc, exec, s[0:1]
	v_readfirstlane_b32 s6, v54
	v_writelane_b32 v254, s79, 26
	s_cbranch_vccnz .LBB0_366
	s_load_dwordx2 s[0:1], s[2:3], 0x70
	v_ashrrev_i32_e32 v130, 4, v54
	v_and_b32_e32 v105, 15, v54
	v_mov_b32_e32 v1, v130
	v_readlane_b32 s4, v253, 42
	s_waitcnt lgkmcnt(0)
	s_add_u32 s90, s0, 0x8c00000
	s_addc_u32 s91, s1, 0
	v_mov_b32_e32 v2, v105
	v_add_u32_e32 v36, s4, v1
	s_lshl_b64 s[4:5], s[64:65], 1
	s_add_u32 s4, s90, s4
	v_lshlrev_b32_e32 v52, 3, v2
	v_lshlrev_b32_e32 v1, s60, v36
	s_addc_u32 s5, s91, s5
	v_ashrrev_i32_e32 v53, 31, v52
	v_add_u32_e32 v40, s62, v1
	v_add_lshl_u32 v1, v36, 32, s60
	v_lshl_add_u64 v[2:3], v[52:53], 1, s[4:5]
	v_add_u32_e32 v1, s62, v1
	v_mad_i64_i32 v[8:9], s[4:5], v1, s33, v[2:3]
	v_add_lshl_u32 v1, v36, 64, s60
	v_add_u32_e32 v1, s62, v1
	v_mad_i64_i32 v[12:13], s[4:5], v1, s33, v[2:3]
	v_add_u32_e32 v1, 0x60, v36
	v_lshlrev_b32_e32 v1, s60, v1
	v_mad_i64_i32 v[4:5], s[4:5], v40, s33, v[2:3]
	v_add_u32_e32 v1, s62, v1
	global_load_dwordx4 v[4:7], v[4:5], off
	s_nop 0
	global_load_dwordx4 v[8:11], v[8:9], off
	v_mad_i64_i32 v[2:3], s[4:5], v1, s33, v[2:3]
	global_load_dwordx4 v[12:15], v[12:13], off
	s_nop 0
	global_load_dwordx4 v[16:19], v[2:3], off
	v_mov_b32_e32 v22, v0
	v_mov_b32_e32 v23, v0
	v_add_u32_e32 v55, 0xffffff80, v36
	v_mov_b32_e32 v20, v0
	v_mov_b32_e32 v21, v0
	v_mov_b64_e32 v[26:27], v[22:23]
	v_cmp_lt_i32_e32 vcc, -1, v55
	v_mov_b64_e32 v[24:25], v[20:21]
	s_and_saveexec_b64 s[4:5], vcc
	s_cbranch_execz .LBB0_313
	v_lshlrev_b32_e32 v1, s60, v55
	v_add_u32_e32 v1, s62, v1
	v_mov_b64_e32 v[2:3], s[90:91]
	v_mad_u64_u32 v[2:3], s[8:9], v1, s33, v[2:3]
	v_lshl_add_u64 v[2:3], s[64:65], 1, v[2:3]
	v_lshl_add_u64 v[2:3], v[52:53], 1, v[2:3]
	global_load_dwordx4 v[24:27], v[2:3], off offset:3072

; __device__ __forceinline__ KParams kparams() { unsigned long long a = (unsigned long long)__builtin_amdgcn_kernarg_segment_ptr(); asm volatile("" : "+s"(a)); return (KParams)a; }
; __device__ __forceinline__ void attn_stream(const int wv, LAS unsigned char* lds, unsigned ldsb, const float* __restrict__ qng, const float* __restrict__ kng, const bf16_t* __restrict__ qkvr, bf16_t* __restrict__ og, float* __restrict__ lse, ...
;     ...
;         if (inext >= count) break;
;         item = inext;
;     }
; __global__ void __launch_bounds__(512, 2) mega(Params p_unused) {
;     ...
;         {
;             KParams kp = kparams(); unsigned char* ws = kp->ws;
;             for (int j = blockIdx.x; j < 512; j += gridDim.x) reta_item(wv, lds, ldsb, WSP(bf16_t, WS_R0), WSP(bf16_t, WS_KV), j);
.LBB0_365:
	s_setprio 0
	v_readlane_b32 s66, v254, 0
	v_readlane_b32 s54, v254, 2
	v_readlane_b32 s56, v254, 4
	v_readlane_b32 s58, v254, 7
	v_readlane_b32 s64, v254, 12
	v_readlane_b32 s80, v254, 27
	v_readlane_b32 s67, v254, 1
	v_readlane_b32 s55, v254, 3
	v_readlane_b32 s57, v254, 5
	v_readlane_b32 s53, v254, 6
	v_readlane_b32 s59, v254, 8
	v_readlane_b32 s61, v254, 9
	v_readlane_b32 s60, v254, 10
	v_readlane_b32 s62, v254, 11
	v_readlane_b32 s65, v254, 13
	v_readlane_b32 s63, v254, 14
	v_readlane_b32 s68, v254, 15
	s_movk_i32 s69, 0xa9
	v_readlane_b32 s70, v254, 16
	v_readlane_b32 s71, v254, 17
	s_movk_i32 s72, 0x2000
	s_movk_i32 s76, 0x7f
	v_readlane_b32 s73, v254, 18
	v_readlane_b32 s74, v254, 19
	s_movk_i32 s75, 0x3000
	v_readlane_b32 s77, v254, 20
	s_mov_b32 s78, 0x80000
	v_readlane_b32 s79, v254, 26
	v_readlane_b32 s81, v254, 28

; __device__ __forceinline__ void retc_stream(const int wv, LAS unsigned char* lds, unsigned ldsb, const float* __restrict__ gn_g, const float* __restrict__ gn_b, const bf16_t* __restrict__ qkvr, const bf16_t* __restrict__ grb, const bf16_t* __restrict__ kv, ...
;     int t_ = TIDX; asm volatile("" : "+v"(t_));
;     const int t = t_, w = __builtin_amdgcn_readfirstlane(t >> 6), lane = t & 63, li = lane & 15, g = lane >> 4;
;     if (first >= count) return;
;     const size_t RS = (size_t)QKVR_LD * 2;
;     const unsigned rsub = (unsigned)w * 2u + ((unsigned)lane >> 5), cc = ((unsigned)lane & 31u) ^ rsub;
;     const size_t goffA = (size_t)rsub * RS + cc * 16;
;     const size_t goffS = (size_t)rsub * 512 + cc * 16;
;     const int q4 = li >> 2, p4 = lane & 3;
;     ...
;     unsigned koff[8], toff[8];
; #pragma unroll
;     for (int s = 0; s < 8; ++s) { koff[s] = (unsigned)li * 512u + ((((unsigned)(4 * s + g)) ^ (unsigned)li) << 4); asm volatile("" : "+v"(koff[s])); }
;     { const unsigned xx = (unsigned)(4 * g + q4) & 15u, ph = (unsigned)p4 >> 1, rb = (unsigned)(4 * g + q4) * 512u + 8u * ((unsigned)p4 & 1u);
; #pragma unroll
;       for (int c = 0; c < 8; ++c) { toff[c] = rb + (((2u * c + ph) ^ xx) << 4); asm volatile("" : "+v"(toff[c])); } }
;     int item = first;
;     RETC_ISSUE(item, 0);
.LBB0_466:
	s_or_b64 exec, exec, s[0:1]
	s_mov_b64 s[2:3], s[56:57]
	v_readlane_b32 s0, v253, 43
	s_waitcnt lgkmcnt(0)
	s_barrier
	s_cmpk_lt_u32 s53, 0x100
	s_cbranch_scc1 .Lprio_c
	s_setprio 1
.Lprio_c:
	v_mbcnt_lo_u32_b32 v1, -1, 0
	v_mbcnt_hi_u32_b32 v1, -1, v1
	v_readlane_b32 s1, v253, 44
	v_add_u32_e32 v191, s53, v1
	s_andn2_b64 vcc, exec, s[0:1]
	v_readfirstlane_b32 s4, v191
	s_cbranch_vccnz .LBB0_504
	s_load_dwordx2 s[0:1], s[2:3], 0x70
	s_load_dwordx4 s[16:19], s[2:3], 0x28
	v_bfe_u32 v2, v191, 5, 1
	v_and_b32_e32 v3, 31, v191
	s_waitcnt vmcnt(0)
	v_mov_b32_e32 v5, v0
	s_waitcnt lgkmcnt(0)
	s_add_u32 s82, s0, 0x8c00000
	s_addc_u32 s39, s1, 0
	s_add_u32 s2, s0, 0x11400000
	v_writelane_b32 v254, s2, 31
	s_addc_u32 s2, s1, 0
	v_writelane_b32 v254, s2, 33
	s_lshl_b64 s[2:3], s[80:81], 1
	s_add_u32 s2, s0, s2
	s_addc_u32 s3, s1, s3
	s_add_u32 s2, s2, 0x15400000
	v_writelane_b32 v254, s2, 35
	s_addc_u32 s2, s3, 0
	s_ashr_i32 s3, s4, 6
	v_writelane_b32 v254, s2, 37
	s_lshl_b32 s2, s3, 1
	v_or_b32_e32 v4, s2, v2
	v_bitop3_b32 v2, s2, v3, v2 bitop3:0x36
	v_bfe_u32 v1, v191, 4, 2
	v_and_b32_e32 v9, 15, v191
	v_lshlrev_b32_e32 v2, 4, v2
	v_mov_b32_e32 v3, v0
	v_lshlrev_b64 v[6:7], 9, v[4:5]
	v_lshl_add_u64 v[2:3], v[6:7], 0, v[2:3]
	v_lshlrev_b32_e32 v5, 9, v9
	v_bitop3_b32 v6, v1, v191, 15 bitop3:0x78
	v_lshl_or_b32 v192, v6, 4, v5
	v_bitop3_b32 v6, v1, v9, 4 bitop3:0x36
	v_lshl_or_b32 v193, v6, 4, v5
	v_bitop3_b32 v6, v1, v9, 8 bitop3:0x36
	v_lshl_or_b32 v194, v6, 4, v5
	v_bitop3_b32 v6, v1, v9, 12 bitop3:0x36
	v_lshl_or_b32 v195, v6, 4, v5
	v_bitop3_b32 v6, v1, v9, 16 bitop3:0x36
	v_lshl_or_b32 v196, v6, 4, v5
	v_bitop3_b32 v6, v1, v9, 20 bitop3:0x36
	v_lshl_or_b32 v197, v6, 4, v5
	v_bitop3_b32 v6, v1, v9, 24 bitop3:0x36
	v_lshl_or_b32 v198, v6, 4, v5
	v_bitop3_b32 v6, v1, v9, 28 bitop3:0x36
	v_lshl_or_b32 v199, v6, 4, v5
	v_bfe_u32 v5, v191, 2, 2
	v_lshlrev_b32_e32 v10, 2, v1
	v_lshlrev_b32_e32 v11, 3, v191
	v_or_b32_e32 v6, v10, v5
	v_bfe_u32 v7, v191, 1, 1
	v_and_b32_e32 v11, 8, v11
	v_lshl_or_b32 v6, v6, 9, v11
	v_bitop3_b32 v11, v10, v7, v5 bitop3:0x36
	v_lshl_or_b32 v200, v11, 4, v6
	v_or_b32_e32 v11, 2, v7
	v_bitop3_b32 v11, v10, v11, v5 bitop3:0x36
	v_lshl_or_b32 v201, v11, 4, v6
	v_or_b32_e32 v11, 4, v7
	v_bitop3_b32 v11, v10, v11, v5 bitop3:0x36
	v_lshl_or_b32 v202, v11, 4, v6
	v_or_b32_e32 v11, 6, v7
	v_bitop3_b32 v11, v10, v11, v5 bitop3:0x36
	v_lshl_or_b32 v203, v11, 4, v6
	v_or_b32_e32 v11, 8, v7
	s_movk_i32 s2, 0x4200
	v_bitop3_b32 v11, v10, v11, v5 bitop3:0x36
	v_mad_u64_u32 v[180:181], s[4:5], v4, s2, v[2:3]
	v_readlane_b32 s2, v253, 59
	v_lshl_or_b32 v204, v11, 4, v6
	v_or_b32_e32 v11, 10, v7
	s_add_u32 s2, s82, s2
	v_bitop3_b32 v11, v10, v11, v5 bitop3:0x36
	s_addc_u32 s5, s39, 0
	v_readlane_b32 s6, v253, 60
	v_lshl_or_b32 v205, v11, 4, v6
	v_or_b32_e32 v11, 12, v7
	v_or_b32_e32 v7, 14, v7
	v_readlane_b32 s7, v253, 61
	s_add_u32 s4, s2, s6
	v_bitop3_b32 v11, v10, v11, v5 bitop3:0x36
	v_bitop3_b32 v5, v10, v7, v5 bitop3:0x36
	s_addc_u32 s5, s5, s7
	s_lshl_b32 s2, s3, 10
	v_lshl_or_b32 v207, v5, 4, v6
	v_lshl_add_u64 v[4:5], s[4:5], 0, v[180:181]
	s_mov_b64 s[4:5], 0x2400
	s_add_i32 s58, s2, 0
	v_lshl_or_b32 v206, v11, 4, v6
	v_lshl_add_u64 v[6:7], v[4:5], 0, s[4:5]
	s_mov_b32 m0, s58
	s_mov_b64 s[4:5], 0x46400
	s_add_i32 s47, s58, 0x2000
	global_load_lds_dwordx4 v[6:7], off nt
	v_lshl_add_u64 v[6:7], v[4:5], 0, s[4:5]
	s_mov_b32 m0, s47
	s_mov_b64 s[4:5], 0x8a400
	s_add_i32 s24, s58, 0x4000
	global_load_lds_dwordx4 v[6:7], off nt
	v_lshl_add_u64 v[6:7], v[4:5], 0, s[4:5]
	s_mov_b32 m0, s24
	s_mov_b64 s[4:5], 0xce400
	s_add_i32 s25, s58, 0x6000
	global_load_lds_dwordx4 v[6:7], off nt
	v_lshl_add_u64 v[6:7], v[4:5], 0, s[4:5]
	s_mov_b32 m0, s25
	s_mov_b64 s[4:5], 0x112400
	s_add_i32 s48, s58, 0x8000
	global_load_lds_dwordx4 v[6:7], off nt
	v_lshl_add_u64 v[6:7], v[4:5], 0, s[4:5]
	s_mov_b32 m0, s48
	s_mov_b64 s[4:5], 0x156400
	s_add_i32 s49, s58, 0xa000
	global_load_lds_dwordx4 v[6:7], off nt
	v_lshl_add_u64 v[6:7], v[4:5], 0, s[4:5]
	s_mov_b32 m0, s49
	s_mov_b64 s[4:5], 0x19a400
	s_add_i32 s50, s58, 0xc000
	global_load_lds_dwordx4 v[6:7], off nt
	v_lshl_add_u64 v[6:7], v[4:5], 0, s[4:5]
	s_mov_b32 m0, s50
	s_mov_b64 s[4:5], 0x1de400
	s_add_i32 s51, s58, 0xe000
	global_load_lds_dwordx4 v[6:7], off nt
	v_lshl_add_u64 v[4:5], v[4:5], 0, s[4:5]
	s_mov_b32 m0, s51
; #define LAS __attribute__((address_space(3)))
; __device__ __forceinline__ void retc_stream(const int wv, LAS unsigned char* lds, unsigned ldsb, const float* __restrict__ gn_g, const float* __restrict__ gn_b, const bf16_t* __restrict__ qkvr, const bf16_t* __restrict__ grb, const bf16_t* __restrict__ kv, ...
;     ...
;     for (int s = 0; s < 8; ++s) { koff[s] = (unsigned)li * 512u + ((((unsigned)(4 * s + g)) ^ (unsigned)li) << 4); asm volatile("" : "+v"(koff[s])); }
;     { const unsigned xx = (unsigned)(4 * g + q4) & 15u, ph = (unsigned)p4 >> 1, rb = (unsigned)(4 * g + q4) * 512u + 8u * ((unsigned)p4 & 1u);
; #pragma unroll
;       for (int c = 0; c < 8; ++c) { toff[c] = rb + (((2u * c + ph) ^ xx) << 4); asm volatile("" : "+v"(toff[c])); } }
;     int item = first;
;     RETC_ISSUE(item, 0);
;     for (;;) {
;         const int h = item >> 6, n = item & 63;
;         const int inext = item + stride;
;         const float lg2 = log2f(1.0f - exp2f(-5.0f - (float)h));
;         WAITV0(); LBAR(); RETC_ISSUE(item, 1);
;         bf16x8 qf[8];
;         { unsigned ib = (unsigned)w * 8192u; asm volatile("" : "+v"(ib));
; #pragma unroll
;         for (int s = 0; s < 8; ++s) qf[s] = *(const LAS bf16x8*)(lds + ib + koff[s]); }
;         WAITV0(); LBAR(); RETC_ISSUE(item, 2);
;         bf16x8 pf[4];
;         {
;             f32x4 sc[8];
;             const int qi = 16 * w + li;
;             unsigned ibk = 65536u; asm volatile("" : "+v"(ibk));
; #pragma unroll
;             for (int kt = 0; kt < 8; ++kt) {
;                 f32x4 a = (f32x4){0.f, 0.f, 0.f, 0.f};
;                 if (kt <= w) {
;                     bf16x8 kf[8];
; #pragma unroll
;                     for (int s = 0; s < 8; ++s) kf[s] = *(const LAS bf16x8*)(lds + ibk + kt * 8192 + koff[s]);
;                     asm volatile("s_waitcnt lgkmcnt(0)" ::: "memory");
; #pragma unroll
;                     for (int s = 0; s < 8; ++s) a = MFMA16(kf[s], qf[s], a);
;                 }
; #pragma unroll
;                 for (int e = 0; e < 4; ++e) { const int kj = 16 * kt + 4 * g + e; a[e] = (kj <= qi) ? a[e] : 0.f; }
;     ...
;         for (int e = 0; e < 4; ++e) {
;             const int q = 16 * w + 4 * g + e;
;             const float xi = exp2f(lg2 * (float)(q - 127));
;             float sum = 0.f;
; #pragma unroll
;             for (int c = 0; c < 32; ++c) { acc[c][e] *= xi; sum += acc[c][e]; }
	s_lshl_b32 s4, s3, 4
	global_load_lds_dwordx4 v[4:5], off nt
	v_or_b32_e32 v4, s4, v9
	v_and_b32_e32 v8, 63, v191
	v_or_b32_e32 v5, s4, v10
	v_cmp_gt_i32_e64 s[4:5], v10, v4
	v_lshlrev_b32_e32 v7, 2, v8
	v_xor_b32_e32 v208, 4, v7
	v_writelane_b32 v254, s4, 39
	v_xor_b32_e32 v209, 8, v7
	v_xor_b32_e32 v210, 16, v7
	v_xor_b32_e32 v211, 32, v7
	v_lshlrev_b32_e32 v7, 1, v9
	v_writelane_b32 v254, s5, 40
	v_cmp_lt_i32_e64 s[4:5], v10, v4
	v_lshl_or_b32 v212, v5, 10, v7
	v_or_b32_e32 v7, 2, v10
	v_writelane_b32 v254, s4, 41
	s_lshl_b32 s2, s3, 13
	s_cmp_gt_i32 s3, -1
	v_writelane_b32 v254, s5, 42
	v_cmp_gt_i32_e64 s[4:5], v7, v4
	v_or_b32_e32 v7, 3, v10
	s_cselect_b64 s[22:23], -1, 0
	v_writelane_b32 v254, s4, 43
	s_cmp_gt_i32 s3, 0
	v_add_u32_e32 v6, 0xffffff81, v5
	v_writelane_b32 v254, s5, 44
	v_cmp_gt_i32_e64 s[4:5], v7, v4
	v_or_b32_e32 v7, 16, v10
	v_cvt_f32_i32_e32 v213, v6
	v_writelane_b32 v254, s4, 45
	v_add_u32_e32 v6, 0xffffff82, v5
	v_cvt_f32_i32_e32 v214, v6
	v_writelane_b32 v254, s5, 46
	s_cselect_b64 s[4:5], -1, 0
	v_writelane_b32 v254, s4, 47
	s_cmp_gt_i32 s3, 1
	s_cselect_b64 s[26:27], -1, 0
	v_writelane_b32 v254, s5, 48
	v_cmp_gt_i32_e64 s[4:5], v7, v4
	v_or_b32_e32 v7, 17, v10
	s_cmp_gt_i32 s3, 2
	v_writelane_b32 v254, s4, 49
	v_add_u32_e32 v6, 0xffffff83, v5
	v_add_u32_e32 v5, 0xffffff84, v5
	v_writelane_b32 v254, s5, 50
	v_cmp_gt_i32_e64 s[4:5], v7, v4
	v_or_b32_e32 v7, 18, v10
	v_cvt_f32_i32_e32 v215, v6
	v_writelane_b32 v254, s4, 51
	v_cvt_f32_i32_e32 v216, v5
	v_or_b32_e32 v8, 64, v10
	v_writelane_b32 v254, s5, 52
	v_cmp_gt_i32_e64 s[4:5], v7, v4
	v_or_b32_e32 v7, 19, v10
	v_or_b32_e32 v9, 0x41, v10
	v_writelane_b32 v254, s4, 53
	v_or_b32_e32 v11, 0x42, v10
	v_or_b32_e32 v12, 0x43, v10
	v_writelane_b32 v254, s5, 54
	v_cmp_gt_i32_e64 s[4:5], v7, v4
	v_or_b32_e32 v7, 32, v10
	v_or_b32_e32 v13, 0x50, v10
	v_writelane_b32 v254, s4, 55
	v_or_b32_e32 v14, 0x51, v10
	v_or_b32_e32 v15, 0x52, v10
	v_writelane_b32 v254, s5, 56
	v_cmp_gt_i32_e64 s[4:5], v7, v4
	v_or_b32_e32 v7, 33, v10
	v_or_b32_e32 v16, 0x53, v10
	v_writelane_b32 v254, s4, 57
	v_or_b32_e32 v17, 0x60, v10
	v_or_b32_e32 v18, 0x61, v10
	v_writelane_b32 v254, s5, 58
	v_cmp_gt_i32_e64 s[4:5], v7, v4
	v_or_b32_e32 v7, 34, v10
	v_or_b32_e32 v19, 0x62, v10
	v_writelane_b32 v254, s4, 59
	v_or_b32_e32 v20, 0x63, v10
	v_or_b32_e32 v21, 0x70, v10
	v_writelane_b32 v254, s5, 60
	v_cmp_gt_i32_e64 s[4:5], v7, v4
	v_or_b32_e32 v7, 35, v10
	v_cmp_gt_i32_e64 s[62:63], v7, v4
	v_writelane_b32 v254, s4, 61
	v_or_b32_e32 v7, 48, v10
	v_cmp_gt_i32_e64 s[64:65], v7, v4
	v_writelane_b32 v254, s5, 62
	s_cselect_b64 s[4:5], -1, 0
	s_cmp_gt_i32 s3, 3
	s_cselect_b64 s[30:31], -1, 0
	s_cmp_gt_i32 s3, 4
	s_cselect_b64 s[34:35], -1, 0
	s_cmp_gt_i32 s3, 5
	s_cselect_b64 s[42:43], -1, 0
	s_cmp_gt_i32 s3, 6
	s_cselect_b64 s[44:45], -1, 0
	s_add_i32 s46, s58, 0x10000
	s_add_i32 s53, s58, 0x12000
	s_add_i32 s52, s58, 0x14000
	s_add_i32 s55, s58, 0x16000
	s_add_i32 s54, s58, 0x18000
	s_add_i32 s57, s58, 0x1a000
	s_add_i32 s56, s58, 0x1c000
	s_add_i32 s59, s58, 0x1e000
	v_readlane_b32 s3, v253, 52
	s_add_u32 s0, s0, s3
	v_readlane_b32 s3, v253, 53
	s_addc_u32 s1, s1, s3
	v_writelane_b32 v254, s4, 63
	v_lshl_add_u64 v[182:183], s[0:1], 0, v[2:3]
	v_or_b32_e32 v2, 49, v10
	v_or_b32_e32 v3, 50, v10
	v_or_b32_e32 v7, 51, v10
	v_or_b32_e32 v22, 0x71, v10
	v_or_b32_e32 v23, 0x72, v10
	v_or_b32_e32 v10, 0x73, v10
	v_lshlrev_b32_e32 v217, 5, v1
	v_writelane_b32 v252, s5, 0
	v_xor_b32_e32 v218, 32, v217
	v_xor_b32_e32 v219, 64, v217
	v_xor_b32_e32 v220, 0x60, v217
	v_mov_b32_e32 v221, s2
	v_readlane_b32 s60, v253, 56
	v_readlane_b32 s61, v253, 54
	s_mov_b32 s28, s66
	v_cmp_gt_i32_e64 s[66:67], v2, v4
	v_cmp_gt_i32_e64 s[68:69], v3, v4
	v_cmp_gt_i32_e64 s[70:71], v7, v4
	v_cmp_gt_i32_e64 s[72:73], v8, v4
	v_cmp_gt_i32_e64 s[74:75], v9, v4
	v_cmp_gt_i32_e64 s[76:77], v11, v4
	v_cmp_gt_i32_e64 s[78:79], v12, v4
	v_cmp_gt_i32_e64 s[80:81], v13, v4
	v_cmp_gt_i32_e64 s[14:15], v14, v4
	v_cmp_gt_i32_e64 s[84:85], v15, v4
	v_cmp_gt_i32_e64 s[86:87], v16, v4
	v_cmp_gt_i32_e64 s[20:21], v17, v4
	v_cmp_gt_i32_e64 s[90:91], v18, v4
	v_cmp_gt_i32_e64 s[92:93], v19, v4
	v_cmp_gt_i32_e64 s[94:95], v20, v4
	v_cmp_gt_i32_e64 s[96:97], v21, v4
	v_cmp_gt_i32_e64 s[4:5], v22, v4
	v_cmp_gt_i32_e64 s[6:7], v23, v4
	v_cmp_gt_i32_e64 s[8:9], v10, v4
	s_branch .LBB0_469

; #define WAITV0() asm volatile("s_waitcnt vmcnt(0)" ::: "memory")
; #define LBAR() do { asm volatile("s_waitcnt lgkmcnt(0)" ::: "memory"); __builtin_amdgcn_s_barrier(); asm volatile("" ::: "memory"); } while (0)
; __device__ __forceinline__ void retc_stream(const int wv, LAS unsigned char* lds, unsigned ldsb, const float* __restrict__ gn_g, const float* __restrict__ gn_b, const bf16_t* __restrict__ qkvr, const bf16_t* __restrict__ grb, const bf16_t* __restrict__ kv, ...
;     ...
;     WAITV0(); LBAR();
; }
.LBB0_503:
	s_setprio 0
	s_waitcnt vmcnt(0)
	s_waitcnt lgkmcnt(0)
	s_barrier
	v_readlane_b32 s66, v254, 0
	v_readlane_b32 s54, v254, 2
	v_readlane_b32 s56, v254, 4
	v_readlane_b32 s58, v254, 7
	v_readlane_b32 s64, v254, 12
	v_readlane_b32 s67, v254, 1
	v_readlane_b32 s55, v254, 3
	v_readlane_b32 s57, v254, 5
	v_readlane_b32 s53, v254, 6
	v_readlane_b32 s59, v254, 8
	v_readlane_b32 s61, v254, 9
	v_readlane_b32 s60, v254, 10
	v_readlane_b32 s62, v254, 11
	v_readlane_b32 s65, v254, 13
	v_readlane_b32 s63, v254, 14
	v_readlane_b32 s68, v254, 15
	s_movk_i32 s69, 0xa9
	v_readlane_b32 s70, v254, 16
	v_readlane_b32 s71, v254, 17
	s_movk_i32 s72, 0x2000
	s_movk_i32 s76, 0x7f
	v_readlane_b32 s73, v254, 18
	v_readlane_b32 s74, v254, 19
	s_movk_i32 s75, 0x3000
	s_movk_i32 s92, 0xc00
	v_readlane_b32 s77, v254, 20
	s_mov_b32 s78, 0x80000
	v_readlane_b32 s79, v254, 26
